# w_in-gap workgroups take 12 instead of 11 conversion jobs each (phase 0 converts 300 fewer jobs), on top of conv gelu folding and barrier set-up de-serialisation
# baseline (speedup 1.0000x reference)
; #define LAS __attribute__((address_space(3)))
; __device__ __forceinline__ int opaque_tid() { int t = threadIdx.x; asm volatile("" : "+v"(t)); return t; }
; template <bool PREPMAP> __device__ __forceinline__ int cvt_map(int q) {
;     if (!PREPMAP) return q;
;     constexpr int NL = (NLAYER - 1) * GAP_PRE;
;     if (q >= NL) return q - NL;
;     return (1 + q / GAP_PRE) * CT_LAYER + q % GAP_PRE;
; }
; template <bool PREPMAP>
; __device__ __forceinline__ void convert_jobs(const Params& p, int job0, int job_end, int stride, LAS unsigned char* lds) {
;     if (job0 >= job_end) return;
;     const int tid = opaque_tid();
;     int job = job0;
;     CvtJob cur = cvt_decode(p, cvt_map<PREPMAP>(job));
.LBB0_11:
	s_or_b64 exec, exec, s[4:5]
	s_mov_b32 s24, s80
	s_cmpk_gt_i32 s80, 0x1466
	s_cbranch_scc1 .LBB0_197
	v_mov_b32_e32 v36, v210
	s_cmpk_lt_i32 s80, 0xe5b
	s_cbranch_scc0 .LBB0_14
	s_mul_hi_i32 s4, s80, 0x357fb0
	s_lshr_b32 s5, s4, 31
	s_ashr_i32 s4, s4, 0
	s_add_i32 s4, s4, s5
	s_mul_i32 s5, s4, 0xc50
	s_mulk_i32 s4, 0x4c9
	s_sub_i32 s4, s80, s4
	s_add_i32 s4, s4, s5
	s_add_i32 s7, s4, 0xc50
	s_cbranch_execz .LBB0_15
	s_branch .LBB0_16
.LBB0_14:
.LBB0_15:
	s_add_i32 s7, s80, 0xfffff1a5
	s_add_i32 s4, s7, 0x384
	s_cmpk_lt_i32 s7, 0x4c9
	s_cselect_b32 s7, s7, s4

; #define LAS __attribute__((address_space(3)))
; __device__ __forceinline__ int opaque_tid() { int t = threadIdx.x; asm volatile("" : "+v"(t)); return t; }
; template <bool PREPMAP> __device__ __forceinline__ int cvt_map(int q) {
;     if (!PREPMAP) return q;
;     constexpr int NL = (NLAYER - 1) * GAP_PRE;
;     if (q >= NL) return q - NL;
;     return (1 + q / GAP_PRE) * CT_LAYER + q % GAP_PRE;
; }
; template <bool PREPMAP>
; __device__ __forceinline__ void convert_jobs(const Params& p, int job0, int job_end, int stride, LAS unsigned char* lds) {
;     if (job0 >= job_end) return;
;     const int tid = opaque_tid();
;     int job = job0;
;     CvtJob cur = cvt_decode(p, cvt_map<PREPMAP>(job));
;     f32x4 v[8]; float gk[8];
;     cvt_load(cur, tid, v, gk);
;     for (;;) {
;         const int nj = job + stride; const bool more = nj < job_end;
;         CvtJob nxt = cur; f32x4 v2[8]; float gk2[8];
;         if (more) { nxt = cvt_decode(p, cvt_map<PREPMAP>(nj)); cvt_load(nxt, tid, v2, gk2); }
.LBB0_106:
	s_load_dwordx2 s[4:5], s[0:1], 0xb0
	s_mov_b64 s[48:49], s[34:35]
	s_mov_b32 s66, s25
	s_mov_b32 s56, s36
	s_mov_b32 s67, s33
	s_waitcnt lgkmcnt(0)
	s_add_i32 s65, s24, s4
	s_cmpk_lt_i32 s65, 0x1467
	s_cselect_b64 s[46:47], -1, 0
	s_cmpk_gt_i32 s65, 0x1466
	s_cselect_b64 s[44:45], -1, 0
	s_and_b64 vcc, exec, s[44:45]
	s_cbranch_vccnz .LBB0_194
	s_cmpk_lt_i32 s65, 0xe5b
	s_mov_b64 s[4:5], -1
	s_cbranch_scc0 .LBB0_109
	s_mul_hi_i32 s4, s65, 0x357fb0
	s_lshr_b32 s5, s4, 31
	s_ashr_i32 s4, s4, 0
	s_add_i32 s4, s4, s5
	s_mul_i32 s5, s4, 0xc50
	s_mulk_i32 s4, 0x4c9
	s_sub_i32 s4, s65, s4
	s_add_i32 s4, s4, s5
	s_add_i32 s7, s4, 0xc50
	s_mov_b64 s[4:5], 0
.LBB0_109:
	s_andn2_b64 vcc, exec, s[4:5]
	s_cbranch_vccnz .LBB0_111
	s_add_i32 s7, s65, 0xfffff1a5
	s_add_i32 s4, s7, 0x384
	s_cmpk_lt_i32 s7, 0x4c9
	s_cselect_b32 s7, s7, s4

; #define LAS __attribute__((address_space(3)))
; __device__ __forceinline__ unsigned xb_ld(unsigned* p)              { return __hip_atomic_load(p, __ATOMIC_RELAXED, __HIP_MEMORY_SCOPE_AGENT); }
; __device__ __forceinline__ void xcd_barrier_complete(unsigned* bar, unsigned x, unsigned& nloc, unsigned& nx) {
;     const unsigned G = gridDim.x * gridDim.y * gridDim.z;
;     unsigned sum, cnt, mine, sp = 0u;
;     for (;;) {
;         sum = 0u; cnt = 0u; mine = 0u;
; #pragma unroll
;         for (unsigned j = 0; j < 16; ++j) { const unsigned c = xb_ld(&bar[XB_XCNT(j)]); sum += c; cnt += (c > 0u) ? 1u : 0u; mine = (j == x) ? c : mine; }
;         if (sum == G) break;
;         __builtin_amdgcn_s_sleep(1);
;         if ((++sp & 255u) == 0u) { if (xb_ld(&bar[XB_TMO])) break; if (sp > XB_SPIN_CAP) { atomicAdd(&bar[XB_TMO], 1u); break; } }
;     }
;     nloc = mine > 0u ? mine : 1u; nx = cnt > 0u ? cnt : 1u;
; __device__ __forceinline__ void run_phase(const Params& pin, int ph, LAS unsigned char* lds, const XcdBarrier& xb) {
;     Params p; p.ws = pin.ws; p.out = pin.out; p.ph_lo = pin.ph_lo; p.ph_hi = pin.ph_hi; asm volatile("" : "+s"(p.ws));
;     { unsigned long long uw = (unsigned long long)p.ws, uo = (unsigned long long)p.out; asm volatile("" : "+s"(uw), "+s"(uo));
;       p.ws = (unsigned char*)(__attribute__((address_space(1))) unsigned char*)uw;
;       p.out = (float*)(__attribute__((address_space(1))) float*)uo; }
;     {
;         const float* const* tab = (const float* const*)(p.ws + WS_PTRS);
; #pragma unroll
;         for (int i = 0; i < 19; ++i) { const unsigned long long v = (unsigned long long)tab[i];
;             const unsigned lo = __builtin_amdgcn_readfirstlane((unsigned)v), hi2 = __builtin_amdgcn_readfirstlane((unsigned)(v >> 32));
;             p.in[i] = (const float*)(const __attribute__((address_space(1))) float*)(((unsigned long long)hi2 << 32) | lo); }
;     }
;     const int layer = (ph - 1) / 9, s = (ph - 1) % 9;
;     unsigned char* wl = p.ws + WS_W + (size_t)layer * WL_SIZE;
;     const float* cosT = (const float*)(p.ws + WS_COS); const float* sinT = (const float*)(p.ws + WS_SIN);
;     float* ssqc = (float*)(p.ws + WS_SSQC);
;     pg8::StaticOrder S;
.LBB0_295:
	s_load_dwordx2 s[20:21], s[0:1], 0xb0
	s_lshl_b32 s4, s80, 9
	v_writelane_b32 v252, s4, 5
	s_mov_b32 s15, 0
	s_mov_b32 s31, s6
	s_waitcnt lgkmcnt(0)
	s_lshl_b32 s4, s20, 3
	s_and_b32 s4, s4, 0x3fffff8
	s_cmpk_gt_i32 s80, 0xff
	v_writelane_b32 v252, s4, 6
	s_cselect_b64 s[4:5], -1, 0
	v_writelane_b32 v252, s4, 7
	s_cmpk_lt_u32 s80, 0x1b0
	s_mov_b32 s86, 0xfff58000
	v_writelane_b32 v252, s5, 8
	s_cselect_b64 s[4:5], -1, 0
	v_writelane_b32 v252, s4, 9
	s_ashr_i32 s7, s20, 31
	s_lshl_b32 s30, s20, 9
	v_writelane_b32 v252, s5, 10
	s_and_b32 s4, s80, 7
	v_writelane_b32 v252, s4, 11
	s_bfe_u32 s4, s80, 0x50003
	v_writelane_b32 v252, s4, 12
	s_lshl_b32 s14, s4, 9
	v_writelane_b32 v252, s14, 13
	s_ashr_i32 s4, s80, 31
	s_mov_b32 s88, 0xfffe0000
	v_writelane_b32 v252, s15, 14
	v_writelane_b32 v252, s4, 15
	s_lshr_b32 s4, s4, 29
	s_add_i32 s5, s80, s4
	s_ashr_i32 s4, s5, 3
	s_and_b32 s5, s5, -8
	s_sub_i32 s5, s80, s5
	s_lshl_b32 s6, s5, 5
	s_cmpk_lt_i32 s80, 0x5ac
	v_writelane_b32 v252, s7, 16
	s_cselect_b64 s[8:9], -1, 0
	v_writelane_b32 v252, s8, 17
	s_mul_i32 s7, s5, 0xb5
	s_add_i32 s7, s7, 4
	v_writelane_b32 v252, s9, 18
	s_add_i32 s8, s80, 0x84d
	v_writelane_b32 v252, s8, 19
	s_and_b32 s8, s80, 0x7fffff80
	s_cmpk_eq_i32 s8, 0x100
	s_cselect_b64 s[8:9], -1, 0
	v_writelane_b32 v252, s8, 20
	v_mov_b32_e32 v211, 0x419c8000
	v_mov_b32_e32 v212, 0x358637bd
	v_writelane_b32 v252, s9, 21
	s_bfe_u32 s8, s80, 0x40003
	s_lshl_b32 s14, s8, 8
	v_writelane_b32 v252, s8, 22
	s_add_u32 s8, s26, 0x419c8800
	s_addc_u32 s9, s27, 0
	s_add_u32 s22, s26, 0x419c8a00
	v_writelane_b32 v252, s8, 23
	s_addc_u32 s23, s27, 0
	v_mov_b32_e32 v213, 1
	v_writelane_b32 v252, s9, 24
	s_add_u32 s8, s26, 0x419c8b00
	s_addc_u32 s9, s27, 0
	v_writelane_b32 v252, s8, 25
	v_mov_b32_e32 v214, 0x3ecc95a3
	v_mov_b64_e32 v[216:217], 0xff
	v_writelane_b32 v252, s9, 26
	s_add_u32 s8, s26, 0x419c8c00
	s_addc_u32 s9, s27, 0
	v_writelane_b32 v252, s8, 27
	v_mov_b32_e32 v218, 0xc50
	v_mov_b32_e32 v219, 0xff800000
	v_writelane_b32 v252, s9, 28
	s_add_u32 s8, s26, 0x419c8d00
	s_addc_u32 s9, s27, 0
	v_writelane_b32 v252, s8, 29
	v_mov_b32_e32 v220, 0x60
	v_mov_b32_e32 v221, 0x7f800000
	v_writelane_b32 v252, s9, 30
	s_add_u32 s8, s26, 0x419c8e00
	s_addc_u32 s9, s27, 0
	v_writelane_b32 v252, s8, 31
	v_mov_b32_e32 v222, 0x7fc00000
	s_movk_i32 s81, 0x2a00
	v_writelane_b32 v252, s9, 32
	s_add_u32 s8, s26, 0x419c8f00
	s_addc_u32 s9, s27, 0
	v_writelane_b32 v252, s8, 33
	s_mov_b64 s[82:83], 0x40000
	s_mov_b64 s[84:85], 0x20000
	v_writelane_b32 v252, s9, 34
	s_add_u32 s8, s26, 0x419c9000
	s_addc_u32 s9, s27, 0
	v_writelane_b32 v252, s8, 35
	s_mov_b32 s87, -1
	s_mov_b32 s89, -1
	v_writelane_b32 v252, s9, 36
	s_add_u32 s8, s26, 0x419c9100
	s_addc_u32 s9, s27, 0
	v_writelane_b32 v252, s8, 37
	s_nop 1
	v_writelane_b32 v252, s9, 38
	s_add_u32 s8, s26, 0x419c9200
	s_addc_u32 s9, s27, 0
	v_writelane_b32 v252, s8, 39
	s_nop 1
	v_writelane_b32 v252, s9, 40
	s_add_u32 s8, s26, 0x419c9300
	s_addc_u32 s9, s27, 0
	v_writelane_b32 v252, s8, 41
	s_nop 1
	v_writelane_b32 v252, s9, 42
	s_add_u32 s8, s26, 0x419c9400
	s_addc_u32 s9, s27, 0
	v_writelane_b32 v252, s8, 43
	s_nop 1
	v_writelane_b32 v252, s9, 44
	s_add_u32 s8, s26, 0x419c9500
	s_addc_u32 s9, s27, 0
	v_writelane_b32 v252, s8, 45
	s_nop 1
	v_writelane_b32 v252, s9, 46
	s_add_u32 s8, s26, 0x419c9600
	s_addc_u32 s9, s27, 0
	v_writelane_b32 v252, s8, 47
	s_nop 1
	v_writelane_b32 v252, s9, 48
	s_add_u32 s8, s26, 0x419c9700
	s_addc_u32 s9, s27, 0
	v_writelane_b32 v252, s8, 49
	s_nop 1
	v_writelane_b32 v252, s9, 50
	s_add_u32 s8, s26, 0x419c9800
	s_addc_u32 s9, s27, 0
	v_writelane_b32 v252, s8, 51
	s_nop 1
	v_writelane_b32 v252, s9, 52
	s_add_u32 s8, s26, 0x419c9900
	s_addc_u32 s9, s27, 0
	v_writelane_b32 v252, s8, 53
	s_cmp_eq_u32 s3, 15
	s_nop 0
	v_writelane_b32 v252, s9, 54
	s_cselect_b64 s[8:9], -1, 0
	v_writelane_b32 v252, s8, 55
	s_cmp_eq_u32 s3, 14
	s_nop 0
	v_writelane_b32 v252, s9, 56
	s_cselect_b64 s[8:9], -1, 0
	v_writelane_b32 v252, s8, 57
	s_cmp_eq_u32 s3, 13
	s_nop 0
	v_writelane_b32 v252, s9, 58
	s_cselect_b64 s[8:9], -1, 0
	v_writelane_b32 v252, s8, 59
	s_cmp_eq_u32 s3, 12
	s_nop 0
	v_writelane_b32 v252, s9, 60
	s_cselect_b64 s[8:9], -1, 0
	v_writelane_b32 v252, s8, 61
	s_cmp_eq_u32 s3, 11
	s_nop 0
	v_writelane_b32 v252, s9, 62
	s_cselect_b64 s[8:9], -1, 0
	v_writelane_b32 v252, s8, 63
	s_cmp_eq_u32 s3, 10
	s_nop 0
	v_writelane_b32 v253, s9, 0
	s_cselect_b64 s[8:9], -1, 0
	v_writelane_b32 v253, s8, 1
	s_cmp_eq_u32 s3, 9
	s_nop 0
	v_writelane_b32 v253, s9, 2
	s_cselect_b64 s[8:9], -1, 0
	v_writelane_b32 v253, s8, 3
	s_cmp_eq_u32 s3, 8
	s_nop 0
	v_writelane_b32 v253, s9, 4
	s_cselect_b64 s[8:9], -1, 0
	v_writelane_b32 v253, s8, 5
	s_cmp_eq_u32 s3, 7
	s_nop 0
	v_writelane_b32 v253, s9, 6
	s_cselect_b64 s[8:9], -1, 0
	v_writelane_b32 v253, s8, 7
	s_cmp_eq_u32 s3, 6
	s_nop 0
	v_writelane_b32 v253, s9, 8
	s_cselect_b64 s[8:9], -1, 0
	v_writelane_b32 v253, s8, 9
	s_cmp_eq_u32 s3, 5
	s_nop 0
	v_writelane_b32 v253, s9, 10
	s_cselect_b64 s[8:9], -1, 0
	v_writelane_b32 v253, s8, 11
	s_cmp_eq_u32 s3, 4
	s_nop 0
	v_writelane_b32 v253, s9, 12
	s_cselect_b64 s[8:9], -1, 0
	v_writelane_b32 v253, s8, 13
	s_cmp_eq_u32 s3, 3
	s_nop 0
	v_writelane_b32 v253, s9, 14
	s_cselect_b64 s[8:9], -1, 0
	v_writelane_b32 v253, s8, 15
	s_cmp_eq_u32 s3, 2
	s_nop 0
	v_writelane_b32 v253, s9, 16
	s_cselect_b64 s[8:9], -1, 0
	v_writelane_b32 v253, s8, 17
	s_cmp_eq_u32 s3, 1
	s_nop 0
	v_writelane_b32 v253, s9, 18
	s_cselect_b64 s[8:9], -1, 0
	v_writelane_b32 v253, s8, 19
	s_cmp_eq_u32 s3, 0
	s_nop 0
	v_writelane_b32 v253, s9, 20
	s_cselect_b64 s[8:9], -1, 0
	s_lshl_b32 s3, s3, 8
; #define LAS __attribute__((address_space(3)))
;     __device__ bool next(int i, Unit& u) const {
;         const long L = (long)i * G + c; if (L >= nwg) return false;
;         int wgid = (int)L; { const int q = nwg / NXCD, r = nwg % NXCD, xcd = wgid % NXCD, off = wgid / NXCD; wgid = (xcd < r ? xcd * (q + 1) : r * (q + 1) + (xcd - r) * q) + off; }
;         const int nig = WGM * nN, gid = wgid / nig, fm = gid * WGM, gsz = (nM - fm) < WGM ? (nM - fm) : WGM;
;         u.pm = fm + ((wgid % nig) % gsz); u.pn = (wgid % nig) / gsz; u.k0t = 0; u.nt = ntk; u.part = -1; return true;
;     }
; __device__ __forceinline__ void convert_gap(const Params& p, int layer, int nwg, int base, int per, LAS unsigned char* lds) {
;     if (layer + 1 >= NLAYER) return;
;     const int G = gridDim.x, c = blockIdx.x, rem = nwg % G;
;     const int limit = base == GAP_PRE ? GAP_BASE6 : CT_LAYER;
;     if (rem == 0) { __syncthreads(); convert_jobs<false>(p, (layer + 1) * CT_LAYER + base + c, (layer + 1) * CT_LAYER + limit, G, lds); return; }
;     if (c < rem) return;
;     const int slot = c - rem, nslots = G - rem;
;     int j0 = base + slot * per, j1 = j0 + per;
;     if (slot == nslots - 1 || j1 > limit) j1 = limit;
	v_writelane_b32 v253, s8, 21
	s_add_u32 s3, s28, s3
	s_nop 0
	v_writelane_b32 v253, s9, 22
	s_addc_u32 s8, s29, 0
	s_add_u32 s10, s3, 0x1400
	s_addc_u32 s11, s8, 0
	v_writelane_b32 v253, s10, 23
	s_nop 1
	v_writelane_b32 v253, s11, 24
	s_add_u32 s10, s3, 0x2400
	s_addc_u32 s11, s8, 0
	v_writelane_b32 v253, s10, 25
	s_add_u32 s8, s26, 0x419cba00
	s_addc_u32 s9, s27, 0
	v_writelane_b32 v253, s11, 26
	v_writelane_b32 v253, s8, 27
	s_mul_i32 s3, s5, 57
	s_nop 0
	v_writelane_b32 v253, s9, 28
	s_add_u32 s8, s26, 0x419cbb00
	s_addc_u32 s9, s27, 0
	v_writelane_b32 v253, s8, 29
	s_cmpk_lt_i32 s80, 0x1ce
	s_mov_b64 s[26:27], 0x80
	v_writelane_b32 v253, s9, 30
	s_cselect_b64 s[8:9], -1, 0
	v_writelane_b32 v253, s8, 31
	s_nop 1
	v_writelane_b32 v253, s9, 32
	s_add_i32 s8, s3, 6
	s_add_i32 s3, s20, -8
	s_cmp_ge_i32 s80, s3
	s_cselect_b64 s[10:11], -1, 0
	s_not_b32 s3, s80
	s_add_i32 s3, s20, s3
	v_writelane_b32 v253, s10, 33
	s_cmpk_lt_i32 s80, 0x2b5
	s_mul_i32 s9, s5, 0x56
	v_writelane_b32 v253, s11, 34
	s_cselect_b64 s[10:11], -1, 0
	v_writelane_b32 v253, s10, 35
	s_add_i32 s9, s9, 5
	s_nop 0
	v_writelane_b32 v253, s11, 36
	s_add_i32 s10, s80, 0x4c9
	v_writelane_b32 v253, s10, 37
	s_cmp_lt_i32 s5, 0
	s_mul_i32 s10, s5, 33
	s_cselect_b32 s6, s10, s6
	s_add_i32 s6, s6, s4
	s_ashr_i32 s10, s6, 31
	s_lshr_b32 s10, s10, 26
	s_add_i32 s10, s6, s10
	s_and_b32 s11, s10, 0xffc0
	s_sub_i32 s6, s6, s11
	s_bfe_i32 s11, s6, 0x80000
	s_bfe_u32 s11, s11, 0x3000c
	s_add_i32 s11, s6, s11
	s_and_b32 s12, s11, 0xf8
	s_sub_i32 s6, s6, s12
	s_ashr_i32 s10, s10, 6
	s_lshl_b32 s10, s10, 3
	s_sext_i32_i8 s6, s6
	s_add_i32 s6, s6, s10
	s_bfe_i32 s10, s11, 0x80000
	s_sext_i32_i16 s10, s10
	s_ashr_i32 s10, s10, 3
	v_writelane_b32 v253, s10, 38
	s_add_i32 s6, s6, 1
	v_writelane_b32 v253, s6, 39
	s_cmp_lt_i32 s5, 4
	s_mul_i32 s6, s5, 0xb6
	s_cselect_b32 s6, s6, s7
	s_add_i32 s6, s6, s4
	s_mul_hi_i32 s7, s6, 0x2e8ba2e9
	s_lshr_b32 s10, s7, 31
	s_ashr_i32 s7, s7, 6
	s_add_i32 s7, s7, s10
	s_mul_i32 s10, s7, 0x160
	s_lshl_b32 s7, s7, 3
	s_sub_i32 s10, s6, s10
	s_sub_i32 s6, 33, s7
	s_min_u32 s11, s6, 8
	s_cmp_lt_i32 s5, 6
	s_mul_i32 s6, s5, 58
	s_cselect_b32 s6, s6, s8
	s_add_i32 s6, s6, s4
	s_mul_hi_i32 s8, s6, 0x92492493
	s_add_i32 s8, s8, s6
	s_lshr_b32 s12, s8, 31
	s_ashr_i32 s8, s8, 6
	s_add_i32 s8, s8, s12
	s_mul_i32 s12, s8, 0x70
	s_lshl_b32 s8, s8, 3
	s_sub_i32 s12, s6, s12
	s_sub_i32 s6, 33, s8
	s_min_u32 s13, s6, 8
	s_cmp_lt_i32 s5, 5
	s_mulk_i32 s5, 0x57
	s_cselect_b32 s5, s5, s9
	v_cvt_f32_ubyte0_e32 v1, s11
	s_add_i32 s5, s5, s4
	v_cvt_f32_i32_e32 v0, s10
	v_rcp_iflag_f32_e32 v2, v1
	s_mul_hi_i32 s4, s5, 0x30c30c31
	s_lshr_b32 s6, s4, 31
	s_ashr_i32 s4, s4, 5
	s_add_i32 s4, s4, s6
	s_lshl_b32 s16, s4, 3
	v_mul_f32_e32 v2, v0, v2
	s_mul_i32 s6, s4, 0xa8
	s_sub_i32 s4, 33, s16
	v_trunc_f32_e32 v2, v2
	s_min_u32 s17, s4, 8
	s_ashr_i32 s4, s10, 30
	v_fma_f32 v0, -v2, v1, v0
	s_sub_i32 s9, s5, s6
	s_or_b32 s6, s4, 1
	v_cmp_ge_f32_e64 s[4:5], |v0|, v1
	v_cvt_i32_f32_e32 v0, v2
	s_and_b64 s[4:5], s[4:5], exec
	s_cselect_b32 s4, s6, 0
	v_cvt_f32_ubyte0_e32 v1, s13
	v_readfirstlane_b32 s5, v0
	s_add_i32 s6, s5, s4
	s_mul_i32 s4, s6, s11
	s_sub_i32 s4, s10, s4
	s_abs_i32 s10, s20
	v_cvt_f32_u32_e32 v0, s10
	s_sub_i32 s5, 0, s10
	s_sext_i32_i16 s4, s4
	s_add_i32 s24, s7, s4
	v_rcp_iflag_f32_e32 v0, v0
	s_mov_b32 s18, s24
	s_ashr_i32 s25, s24, 31
	v_rcp_iflag_f32_e32 v2, v1
	v_mul_f32_e32 v0, 0x4f7ffffe, v0
	v_cvt_u32_f32_e32 v0, v0
	s_nop 0
	v_readfirstlane_b32 s11, v0
	s_mul_i32 s5, s5, s11
	s_mul_hi_u32 s5, s11, s5
	s_add_i32 s11, s11, s5
	s_bfe_i64 s[4:5], s[6:7], 0x100000
	s_lshl_b64 s[4:5], s[4:5], 20
	v_writelane_b32 v253, s4, 40
	v_cvt_f32_i32_e32 v0, s12
	v_mul_f32_e32 v2, v0, v2
	v_writelane_b32 v253, s5, 41
	s_mul_hi_u32 s4, s11, 0x5ac
	s_mul_i32 s4, s4, s10
	s_sub_i32 s4, 0x5ac, s4
	v_writelane_b32 v253, s18, 42
	s_sub_i32 s5, s4, s10
	v_trunc_f32_e32 v2, v2
	v_writelane_b32 v253, s19, 43
	s_lshl_b64 s[18:19], s[24:25], 20
	s_cmp_ge_u32 s4, s10
	s_cselect_b32 s4, s5, s4
	s_sub_i32 s5, s4, s10
	s_cmp_ge_u32 s4, s10
	s_cselect_b32 s4, s5, s4
	v_writelane_b32 v253, s18, 44
	s_cmp_lg_u32 s4, 0
	v_fma_f32 v0, -v2, v1, v0
	v_writelane_b32 v253, s19, 45
	s_cselect_b64 s[18:19], -1, 0
	v_writelane_b32 v253, s18, 46
	s_cmp_ge_i32 s80, s4
	s_nop 0
	v_writelane_b32 v253, s19, 47
	s_cselect_b64 s[18:19], -1, 0
	s_sub_i32 s5, s80, s4
; #define LAS __attribute__((address_space(3)))
;     __device__ bool next(int i, Unit& u) const {
;         const long L = (long)i * G + c; if (L >= nwg) return false;
;         int wgid = (int)L; { const int q = nwg / NXCD, r = nwg % NXCD, xcd = wgid % NXCD, off = wgid / NXCD; wgid = (xcd < r ? xcd * (q + 1) : r * (q + 1) + (xcd - r) * q) + off; }
;         const int nig = WGM * nN, gid = wgid / nig, fm = gid * WGM, gsz = (nM - fm) < WGM ? (nM - fm) : WGM;
;         u.pm = fm + ((wgid % nig) % gsz); u.pn = (wgid % nig) / gsz; u.k0t = 0; u.nt = ntk; u.part = -1; return true;
;     }
; __device__ __forceinline__ void convert_gap(const Params& p, int layer, int nwg, int base, int per, LAS unsigned char* lds) {
;     if (layer + 1 >= NLAYER) return;
;     const int G = gridDim.x, c = blockIdx.x, rem = nwg % G;
;     const int limit = base == GAP_PRE ? GAP_BASE6 : CT_LAYER;
;     if (rem == 0) { __syncthreads(); convert_jobs<false>(p, (layer + 1) * CT_LAYER + base + c, (layer + 1) * CT_LAYER + limit, G, lds); return; }
;     if (c < rem) return;
;     const int slot = c - rem, nslots = G - rem;
;     int j0 = base + slot * per, j1 = j0 + per;
;     if (slot == nslots - 1 || j1 > limit) j1 = limit;
;     if (j0 > limit) j0 = limit;
;     __syncthreads();
;     convert_jobs<false>(p, (layer + 1) * CT_LAYER + j0, (layer + 1) * CT_LAYER + j1, 1, lds);
; }
	v_writelane_b32 v253, s18, 48
	s_mul_i32 s7, s5, 13
	s_not_b32 s4, s4
	v_writelane_b32 v253, s19, 49
	s_min_u32 s18, s7, 0x3f6
	s_add_i32 s4, s20, s4
	s_addk_i32 s18, 0x85a
	s_cmp_lg_u32 s5, s4
	s_cselect_b32 s5, s18, 0xc50
	s_min_u32 s4, s7, 0x403
	s_addk_i32 s4, 0x84d
	v_writelane_b32 v253, s5, 50
	s_cmp_lt_u32 s4, s5
	v_writelane_b32 v253, s4, 51
	s_cselect_b64 s[4:5], -1, 0
	v_writelane_b32 v253, s4, 52
	s_nop 1
	v_writelane_b32 v253, s5, 53
	s_ashr_i32 s4, s12, 30
	s_or_b32 s7, s4, 1
	v_cmp_ge_f32_e64 s[4:5], |v0|, v1
	v_cvt_i32_f32_e32 v0, v2
	s_and_b64 s[4:5], s[4:5], exec
	v_cvt_f32_ubyte0_e32 v1, s17
	s_cselect_b32 s4, s7, 0
	v_readfirstlane_b32 s5, v0
	v_cvt_f32_i32_e32 v0, s9
	v_rcp_iflag_f32_e32 v2, v1
	s_add_i32 s7, s5, s4
	s_mul_i32 s4, s7, s13
	s_sub_i32 s4, s12, s4
	s_sext_i32_i8 s4, s4
	v_mul_f32_e32 v2, v0, v2
	s_add_i32 s4, s8, s4
	v_trunc_f32_e32 v2, v2
	v_writelane_b32 v253, s4, 54
	s_ashr_i32 s4, s9, 30
	v_fma_f32 v0, -v2, v1, v0
	s_or_b32 s8, s4, 1
	v_cmp_ge_f32_e64 s[4:5], |v0|, v1
	v_cvt_i32_f32_e32 v0, v2
	s_and_b64 s[4:5], s[4:5], exec
	s_cselect_b32 s4, s8, 0
	v_mov_b32_e32 v1, 0
	v_readfirstlane_b32 s5, v0
	s_add_i32 s8, s5, s4
	s_mul_i32 s4, s8, s17
	s_sub_i32 s4, s9, s4
	s_sext_i32_i16 s4, s4
	s_add_i32 s4, s16, s4
	v_writelane_b32 v253, s4, 55
	s_mul_hi_u32 s4, s11, 0x2b5
	s_mul_i32 s4, s4, s10
	s_sub_i32 s4, 0x2b5, s4
	s_sub_i32 s5, s4, s10
	s_cmp_ge_u32 s4, s10
	s_cselect_b32 s4, s5, s4
	s_sub_i32 s5, s4, s10
	s_cmp_ge_u32 s4, s10
	s_cselect_b32 s4, s5, s4
	s_cmp_lg_u32 s4, 0
	s_cselect_b64 s[10:11], -1, 0
	v_writelane_b32 v253, s10, 56
	s_cmp_ge_i32 s80, s4
	v_mbcnt_lo_u32_b32 v0, -1, 0
	v_writelane_b32 v253, s11, 57
	s_cselect_b64 s[10:11], -1, 0
	s_sub_i32 s5, s80, s4
	v_writelane_b32 v253, s10, 58
	s_mul_i32 s9, s5, 12
	s_not_b32 s4, s4
	v_writelane_b32 v253, s11, 59
	s_min_u32 s10, s9, 0x378
	s_add_i32 s4, s20, s4
	s_addk_i32 s10, 0x4d5
	s_cmp_lg_u32 s5, s4
	s_mul_i32 s4, s21, s20
	s_mul_i32 s47, s4, s2
	s_sext_i32_i16 s2, s6
	v_writelane_b32 v253, s2, 60
	s_sext_i32_i8 s2, s7
	v_writelane_b32 v253, s2, 61
	s_sext_i32_i16 s2, s8
	s_mul_hi_i32 s5, s3, 0x2100
	s_mul_i32 s4, s3, 0x2100
	v_writelane_b32 v253, s2, 62
	s_cselect_b32 s3, s10, 0x84d
	s_min_u32 s2, s9, 0x384
	s_addk_i32 s2, 0x4c9
	v_writelane_b32 v254, s2, 0
	s_cmp_lt_u32 s2, s3
	v_writelane_b32 v254, s14, 1
	v_writelane_b32 v253, s3, 63
	s_cselect_b64 s[2:3], -1, 0
	v_writelane_b32 v254, s15, 2
	v_writelane_b32 v254, s2, 3
	s_and_b32 s14, s20, 0x7fffff
	s_lshl_b32 s25, s20, 12
	v_writelane_b32 v254, s3, 4
	s_lshl_b32 s2, s14, 4
	s_addk_i32 s2, 0xff
	v_writelane_b32 v254, s2, 5
	s_lshl_b64 s[2:3], s[4:5], 2
	v_writelane_b32 v254, s2, 6
	s_load_dwordx4 s[4:7], s[0:1], 0x98
	s_lshl_b64 s[0:1], s[14:15], 15
	v_writelane_b32 v254, s3, 7
	s_lshl_b32 s2, s80, 12
	v_writelane_b32 v254, s2, 8
	s_mul_i32 s2, s14, 0x15000
	v_writelane_b32 v254, s2, 9
	s_add_i32 s2, 0, 0x1fff0
	v_writelane_b32 v254, s2, 10
	s_add_i32 s2, 0, 0x10100
	v_writelane_b32 v254, s2, 11
	s_add_i32 s2, 0, 0x20004
	v_writelane_b32 v254, s2, 12
	s_waitcnt lgkmcnt(0)
	v_writelane_b32 v254, s4, 13
	v_mbcnt_hi_u32_b32 v215, -1, v0
	s_nop 0
	v_writelane_b32 v254, s5, 14
	v_writelane_b32 v254, s6, 15
	v_writelane_b32 v254, s7, 16
	v_writelane_b32 v254, s0, 17
	s_nop 1
	v_writelane_b32 v254, s1, 18
	s_lshl_b64 s[0:1], s[14:15], 16
	v_writelane_b32 v254, s0, 19
	s_nop 1
	v_writelane_b32 v254, s1, 20
	s_lshl_b64 s[0:1], s[14:15], 14
	v_writelane_b32 v254, s0, 21
	s_nop 1
	v_writelane_b32 v254, s1, 22
	v_writelane_b32 v254, s30, 23
	v_writelane_b32 v254, s47, 24
	v_writelane_b32 v254, s25, 25
	v_writelane_b32 v254, s22, 26
	s_nop 1
	v_writelane_b32 v254, s23, 27
	v_readlane_b32 s100, v254, 15
	v_readlane_b32 s101, v254, 16
	s_nop 1
	s_add_u32 s100, s100, 0x419c8500
	s_addc_u32 s101, s101, 0
	global_load_dwordx4 v[160:163], v1, s[100:101]
	global_load_dwordx4 v[164:167], v1, s[100:101] offset:16
	global_load_dwordx4 v[168:171], v1, s[100:101] offset:32
	global_load_dwordx4 v[172:175], v1, s[100:101] offset:48
	global_load_dwordx4 v[176:179], v1, s[100:101] offset:64
	global_load_dwordx4 v[180:183], v1, s[100:101] offset:80
	global_load_dwordx4 v[184:187], v1, s[100:101] offset:96
	global_load_dwordx4 v[188:191], v1, s[100:101] offset:112
	global_load_dwordx4 v[192:195], v1, s[100:101] offset:128
	global_load_dwordx2 v[196:197], v1, s[100:101] offset:144
	s_branch .LBB0_299
